# baseline (speedup 1.0000x reference)
; __device__ __forceinline__ float bflo(unsigned w) { return __uint_as_float(w << 16); }
; __device__ __forceinline__ float bfhi(unsigned w) { return __uint_as_float(w & 0xffff0000u); }
; __device__ __forceinline__ float lane_read(float v, int src) { return __int_as_float(__builtin_amdgcn_ds_bpermute(src << 2, __float_as_int(v))); }
; __device__ __forceinline__ void load_q_roped(const bf16_t* Qw, const float* __restrict__ wq, const float* __restrict__ RT, int pr, int pc, int hi, int lane, bf16x8 (&qr)[8]) {
;   float y[8][8]; float ss = 0.f;
; #pragma unroll
;   for (int d0 = 0; d0 < 8; ++d0) { const u32x4 w = *(const u32x4*)(Qw + d0 * 16);
; #pragma unroll
;     for (int q = 0; q < 4; ++q) { y[d0][2 * q] = bflo(w[q]); y[d0][2 * q + 1] = bfhi(w[q]); } }
; #pragma unroll
;   for (int d0 = 0; d0 < 8; ++d0)
; #pragma unroll
;     for (int e = 0; e < 8; ++e) ss += y[d0][e] * y[d0][e];
;   ss += lane_read(ss, lane ^ 32);
;   const float rstd = __builtin_amdgcn_rsqf(ss * (1.f / 128.f) + 1e-6f);
; #pragma unroll
;   for (int d0 = 0; d0 < 8; ++d0) { const f32x4 w0 = *(const f32x4*)(wq + d0 * 16), w1 = *(const f32x4*)(wq + d0 * 16 + 4);
; #pragma unroll
;     for (int e = 0; e < 8; ++e) y[d0][e] *= rstd * (e < 4 ? w0[e & 3] : w1[e & 3]); }
.LBB0_259:
	s_bfe_u32 s1, s2, 0x10008
	s_ashr_i32 s0, s2, 9
	s_lshl_b32 s3, s1, 8
	v_readlane_b32 s6, v255, 9
	v_readlane_b32 s7, v255, 10
	s_add_u32 s40, s6, s3
	s_addc_u32 s41, s7, 0
	v_readlane_b32 s6, v255, 5
	v_readlane_b32 s7, v255, 6
	s_add_u32 s42, s6, s3
	s_addc_u32 s43, s7, 0
	s_lshl_b32 s3, s2, 6
	s_and_b32 s3, s3, 0x3f00
	v_add_u32_e32 v191, s3, v172
	v_or_b32_e32 v21, v191, v163
	s_lshl_b32 s3, s0, 14
	v_add_u32_e32 v2, s3, v21
	s_lshl_b32 s4, s2, 7
	v_ashrrev_i32_e32 v3, 31, v2
	s_lshl_b32 s1, s1, 9
	s_and_b32 s4, s4, 0x180
	v_lshlrev_b64 v[2:3], 11, v[2:3]
	s_or_b32 s30, s1, s4
	v_lshl_add_u64 v[2:3], s[20:21], 0, v[2:3]
	s_lshl_b32 s4, s30, 1
	v_lshl_add_u64 v[2:3], v[2:3], 0, s[4:5]
	v_lshlrev_b32_e32 v0, 1, v162
	v_lshl_add_u64 v[18:19], v[2:3], 0, v[0:1]
	global_load_dwordx4 v[58:61], v[18:19], off offset:160
	global_load_dwordx4 v[62:65], v[18:19], off offset:224
	global_load_dwordx4 v[66:69], v[18:19], off offset:128
	global_load_dwordx4 v[70:73], v[18:19], off offset:192
	global_load_dwordx4 v[2:5], v[164:165], off
	global_load_dwordx4 v[6:9], v[164:165], off offset:16
	global_load_dwordx4 v[10:13], v[164:165], off offset:64
	global_load_dwordx4 v[82:85], v[164:165], off offset:80
	global_load_dwordx4 v[86:89], v[164:165], off offset:128
	global_load_dwordx4 v[90:93], v[164:165], off offset:144
	global_load_dwordx4 v[94:97], v[164:165], off offset:192
	global_load_dwordx4 v[98:101], v[164:165], off offset:208
	global_load_dwordx4 v[102:105], v[164:165], off offset:256
	global_load_dwordx4 v[106:109], v[164:165], off offset:272
	global_load_dwordx4 v[50:53], v[18:19], off offset:32
	global_load_dwordx4 v[110:113], v[164:165], off offset:320
	global_load_dwordx4 v[114:117], v[164:165], off offset:336
	global_load_dwordx4 v[54:57], v[18:19], off offset:96
	global_load_dwordx4 v[118:121], v[164:165], off offset:384
	global_load_dwordx4 v[122:125], v[164:165], off offset:400
	global_load_dwordx4 v[126:129], v[164:165], off offset:448
	global_load_dwordx4 v[14:17], v[164:165], off offset:464
	global_load_dwordx4 v[74:77], v[18:19], off
	s_lshl_b32 s4, s0, 4
	s_add_i32 s31, s4, 0x8000
	v_ashrrev_i32_e32 v0, 1, v191
	s_movk_i32 s4, 0xffe0
	v_and_or_b32 v20, v0, s4, v162
	v_lshlrev_b32_e32 v0, 5, v21
	v_ashrrev_i32_e32 v21, 31, v20
	v_or_b32_e32 v22, 16, v20
	v_lshl_add_u64 v[20:21], v[20:21], 3, s[48:49]
	global_load_dwordx4 v[78:81], v[18:19], off offset:64
	global_load_dwordx4 v[30:33], v[20:21], off offset:48
	global_load_dwordx4 v[38:41], v[20:21], off offset:32
	global_load_dwordx4 v[42:45], v[20:21], off offset:16
	global_load_dwordx4 v[46:49], v[20:21], off
	s_movk_i32 s4, 0x7e0
	v_and_or_b32 v0, v0, s4, v162
	v_lshlrev_b32_e32 v195, 3, v0
	v_mov_b32_e32 v196, v245
	v_mov_b64_e32 v[244:245], v[242:243]
	v_mov_b64_e32 v[174:175], v[248:249]
	v_ashrrev_i32_e32 v23, 31, v22
	v_lshl_add_u64 v[34:35], v[22:23], 3, s[48:49]
	global_load_dwordx4 v[18:21], v[34:35], off offset:48
	global_load_dwordx4 v[22:25], v[34:35], off offset:32
	global_load_dwordx4 v[26:29], v[34:35], off offset:16
	s_nop 0
	global_load_dwordx4 v[34:37], v[34:35], off
	s_ashr_i32 s1, s0, 31
	s_lshl_b64 s[90:91], s[0:1], 14
	s_ashr_i32 s44, s31, 31
	s_lshl_b64 s[0:1], s[0:1], 23
	s_add_u32 s6, s42, s0
	s_addc_u32 s7, s43, s1
	s_add_u32 s8, s40, s0
	s_addc_u32 s9, s41, s1
	s_mov_b32 s4, s5
	s_mov_b32 s10, s5
	s_mov_b32 s11, s5
	s_mov_b32 s12, s5
	s_mov_b32 s13, s5
	s_mov_b32 s14, s5
	s_mov_b32 s15, s5
	s_mov_b32 s16, s5
	s_mov_b32 s17, s5
	s_mov_b32 s18, s5
	s_mov_b32 s19, s5
	s_mov_b32 s28, 1
	s_waitcnt vmcnt(0)
	v_lshlrev_b32_e32 v142, 16, v58
	v_and_b32_e32 v143, 0xffff0000, v58
	v_lshlrev_b32_e32 v226, 16, v66
	v_and_b32_e32 v227, 0xffff0000, v66
	v_lshlrev_b32_e32 v218, 16, v67
	v_and_b32_e32 v219, 0xffff0000, v67
	v_pk_mul_f32 v[66:67], v[226:227], v[226:227]
	v_pk_mul_f32 v[222:223], v[218:219], v[218:219]
	v_lshlrev_b32_e32 v214, 16, v68
	v_and_b32_e32 v215, 0xffff0000, v68
	v_lshlrev_b32_e32 v144, 16, v69
	v_and_b32_e32 v145, 0xffff0000, v69
	v_pk_mul_f32 v[68:69], v[214:215], v[214:215]
	v_pk_mul_f32 v[210:211], v[144:145], v[144:145]
	v_lshlrev_b32_e32 v202, 16, v51
	v_and_b32_e32 v203, 0xffff0000, v51
	v_lshlrev_b32_e32 v150, 16, v50
	v_and_b32_e32 v151, 0xffff0000, v50
	v_lshlrev_b32_e32 v238, 16, v52
	v_and_b32_e32 v239, 0xffff0000, v52
	v_lshlrev_b32_e32 v230, 16, v53
	v_and_b32_e32 v231, 0xffff0000, v53
	v_lshlrev_b32_e32 v158, 16, v74
	v_and_b32_e32 v159, 0xffff0000, v74
	v_lshlrev_b32_e32 v156, 16, v75
	v_and_b32_e32 v157, 0xffff0000, v75
	v_pk_mul_f32 v[50:51], v[158:159], v[158:159]
	v_lshlrev_b32_e32 v154, 16, v76
	v_add_f32_e32 v0, v50, v51
	v_pk_mul_f32 v[50:51], v[156:157], v[156:157]
	v_and_b32_e32 v155, 0xffff0000, v76
	v_add_f32_e32 v0, v50, v0
	v_add_f32_e32 v0, v51, v0
	v_pk_mul_f32 v[50:51], v[154:155], v[154:155]
	v_lshlrev_b32_e32 v152, 16, v77
	v_and_b32_e32 v153, 0xffff0000, v77
	v_add_f32_e32 v0, v50, v0
	v_add_f32_e32 v0, v51, v0
	v_pk_mul_f32 v[50:51], v[152:153], v[152:153]
	v_pk_mul_f32 v[52:53], v[238:239], v[238:239]
	v_add_f32_e32 v0, v50, v0
	v_add_f32_e32 v0, v51, v0
	v_pk_mul_f32 v[50:51], v[150:151], v[150:151]
	v_pk_mul_f32 v[234:235], v[230:231], v[230:231]
	v_add_f32_e32 v0, v50, v0
	v_add_f32_e32 v0, v51, v0
	v_pk_mul_f32 v[50:51], v[202:203], v[202:203]
	v_lshlrev_b32_e32 v242, 16, v78
	v_add_f32_e32 v0, v50, v0
	v_add_f32_e32 v0, v51, v0
	v_add_f32_e32 v0, v52, v0
	v_add_f32_e32 v0, v53, v0
	v_and_b32_e32 v243, 0xffff0000, v78
	v_add_f32_e32 v0, v234, v0
	v_lshlrev_b32_e32 v198, 16, v55
	v_and_b32_e32 v199, 0xffff0000, v55
	v_lshlrev_b32_e32 v200, 16, v54
	v_and_b32_e32 v201, 0xffff0000, v54
; __device__ __forceinline__ float lane_read(float v, int src) { return __int_as_float(__builtin_amdgcn_ds_bpermute(src << 2, __float_as_int(v))); }
; __device__ __forceinline__ void load_q_roped(const bf16_t* Qw, const float* __restrict__ wq, const float* __restrict__ RT, int pr, int pc, int hi, int lane, bf16x8 (&qr)[8]) {
;     ...
; #pragma unroll
;   for (int d0 = 0; d0 < 8; ++d0)
; #pragma unroll
;     for (int e = 0; e < 8; ++e) ss += y[d0][e] * y[d0][e];
;   ss += lane_read(ss, lane ^ 32);
;   const float rstd = __builtin_amdgcn_rsqf(ss * (1.f / 128.f) + 1e-6f);
; #pragma unroll
;   for (int d0 = 0; d0 < 8; ++d0) { const f32x4 w0 = *(const f32x4*)(wq + d0 * 16), w1 = *(const f32x4*)(wq + d0 * 16 + 4);
; #pragma unroll
;     for (int e = 0; e < 8; ++e) y[d0][e] *= rstd * (e < 4 ? w0[e & 3] : w1[e & 3]); }
; #pragma unroll
;   for (int hf = 0; hf < 2; ++hf)
; #pragma unroll
;     for (int lo = 0; lo < 2; ++lo) { const int d0 = hf * 4 + lo;
;       const float* tp = RT + (size_t)((hf ? pc : pr) * 32 + lo * 16 + hi * 8) * 2;
;       f32x4 t[4];
; #pragma unroll
;       for (int q = 0; q < 4; ++q) t[q] = *(const f32x4*)(tp + 4 * q);
; #pragma unroll
;       for (int e = 0; e < 8; ++e) { const float cs = t[e >> 1][(e & 1) * 2], sn = t[e >> 1][(e & 1) * 2 + 1];
;         const float x1 = y[d0][e], x2 = y[d0 + 2][e]; y[d0][e] = x1 * cs - x2 * sn; y[d0 + 2][e] = x1 * sn + x2 * cs; } }
	v_add_f32_e32 v0, v235, v0
	v_pk_mul_f32 v[54:55], v[242:243], v[242:243]
	v_lshlrev_b32_e32 v248, 16, v79
	v_and_b32_e32 v249, 0xffff0000, v79
	v_add_f32_e32 v0, v54, v0
	v_add_f32_e32 v0, v55, v0
	v_pk_mul_f32 v[54:55], v[248:249], v[248:249]
	v_lshlrev_b32_e32 v206, 16, v80
	v_and_b32_e32 v207, 0xffff0000, v80
	v_add_f32_e32 v0, v54, v0
	v_add_f32_e32 v0, v55, v0
	v_pk_mul_f32 v[54:55], v[206:207], v[206:207]
	v_lshlrev_b32_e32 v204, 16, v81
	v_and_b32_e32 v205, 0xffff0000, v81
	v_add_f32_e32 v0, v54, v0
	v_add_f32_e32 v0, v55, v0
	v_pk_mul_f32 v[54:55], v[204:205], v[204:205]
	v_pk_mul_f32 v[52:53], v[200:201], v[200:201]
	v_add_f32_e32 v0, v54, v0
	v_add_f32_e32 v0, v55, v0
	v_add_f32_e32 v0, v52, v0
	v_pk_mul_f32 v[50:51], v[198:199], v[198:199]
	v_add_f32_e32 v0, v53, v0
	v_lshlrev_b32_e32 v240, 16, v56
	v_and_b32_e32 v241, 0xffff0000, v56
	v_add_f32_e32 v0, v50, v0
	v_lshlrev_b32_e32 v232, 16, v57
	v_and_b32_e32 v233, 0xffff0000, v57
	v_pk_mul_f32 v[56:57], v[240:241], v[240:241]
	v_add_f32_e32 v0, v51, v0
	v_add_f32_e32 v0, v56, v0
	v_pk_mul_f32 v[236:237], v[232:233], v[232:233]
	v_add_f32_e32 v0, v57, v0
	v_add_f32_e32 v0, v236, v0
	v_add_f32_e32 v0, v237, v0
	v_add_f32_e32 v0, v66, v0
	v_add_f32_e32 v0, v67, v0
	v_add_f32_e32 v0, v222, v0
	v_add_f32_e32 v0, v223, v0
	v_add_f32_e32 v0, v68, v0
	v_add_f32_e32 v0, v69, v0
	v_add_f32_e32 v0, v210, v0
	v_pk_mul_f32 v[168:169], v[142:143], v[142:143]
	v_add_f32_e32 v0, v211, v0
	v_lshlrev_b32_e32 v138, 16, v59
	v_and_b32_e32 v139, 0xffff0000, v59
	v_add_f32_e32 v0, v168, v0
	v_pk_mul_f32 v[148:149], v[138:139], v[138:139]
	v_add_f32_e32 v0, v169, v0
	v_lshlrev_b32_e32 v136, 16, v60
	v_and_b32_e32 v137, 0xffff0000, v60
	v_add_f32_e32 v0, v148, v0
	v_lshlrev_b32_e32 v140, 16, v63
	v_and_b32_e32 v141, 0xffff0000, v63
	v_lshlrev_b32_e32 v146, 16, v62
	v_and_b32_e32 v147, 0xffff0000, v62
	v_pk_mul_f32 v[62:63], v[136:137], v[136:137]
	v_add_f32_e32 v0, v149, v0
	v_lshlrev_b32_e32 v134, 16, v61
	v_and_b32_e32 v135, 0xffff0000, v61
	v_add_f32_e32 v0, v62, v0
	v_pk_mul_f32 v[58:59], v[134:135], v[134:135]
	v_add_f32_e32 v0, v63, v0
	v_lshlrev_b32_e32 v228, 16, v70
	v_and_b32_e32 v229, 0xffff0000, v70
	v_add_f32_e32 v0, v58, v0
	v_lshlrev_b32_e32 v220, 16, v71
	v_and_b32_e32 v221, 0xffff0000, v71
	v_pk_mul_f32 v[70:71], v[228:229], v[228:229]
	v_add_f32_e32 v0, v59, v0
	v_add_f32_e32 v0, v70, v0
	v_pk_mul_f32 v[224:225], v[220:221], v[220:221]
	v_add_f32_e32 v0, v71, v0
	v_lshlrev_b32_e32 v216, 16, v72
	v_and_b32_e32 v217, 0xffff0000, v72
	v_add_f32_e32 v0, v224, v0
	v_lshlrev_b32_e32 v192, 16, v73
	v_and_b32_e32 v193, 0xffff0000, v73
	v_pk_mul_f32 v[72:73], v[216:217], v[216:217]
	v_add_f32_e32 v0, v225, v0
	v_add_f32_e32 v0, v72, v0
	v_pk_mul_f32 v[212:213], v[192:193], v[192:193]
	v_add_f32_e32 v0, v73, v0
	v_add_f32_e32 v0, v212, v0
	v_pk_mul_f32 v[170:171], v[146:147], v[146:147]
	v_add_f32_e32 v0, v213, v0
	v_add_f32_e32 v0, v170, v0
	v_pk_mul_f32 v[160:161], v[140:141], v[140:141]
	v_add_f32_e32 v0, v171, v0
	v_lshlrev_b32_e32 v132, 16, v64
	v_and_b32_e32 v133, 0xffff0000, v64
	v_add_f32_e32 v0, v160, v0
	v_lshlrev_b32_e32 v130, 16, v65
	v_and_b32_e32 v131, 0xffff0000, v65
	v_pk_mul_f32 v[64:65], v[132:133], v[132:133]
	v_add_f32_e32 v0, v161, v0
	v_add_f32_e32 v0, v64, v0
	v_pk_mul_f32 v[60:61], v[130:131], v[130:131]
	v_add_f32_e32 v0, v65, v0
	v_add_f32_e32 v0, v60, v0
	v_add_f32_e32 v0, v61, v0
	ds_bpermute_b32 v50, v252, v0
	global_load_dwordx4 v[66:69], v195, s[48:49] offset:48
	global_load_dwordx4 v[70:73], v195, s[48:49] offset:32
	global_load_dwordx4 v[74:77], v195, s[48:49] offset:16
	global_load_dwordx4 v[78:81], v195, s[48:49]
	v_add_u32_e32 v168, 0, v176
	v_add_u32_e32 v169, 0, v177
	v_lshl_add_u64 v[170:171], s[40:41], 0, v[166:167]
	s_waitcnt lgkmcnt(0)
	v_add_f32_e32 v0, v0, v50
	v_mov_b32_e32 v50, 0x358637bd
	v_fmamk_f32 v0, v0, 0x3c000000, v50
	v_rsq_f32_e32 v0, v0
	global_load_dwordx4 v[50:53], v195, s[48:49] offset:176
	global_load_dwordx4 v[54:57], v195, s[48:49] offset:160
	global_load_dwordx4 v[58:61], v195, s[48:49] offset:144
	global_load_dwordx4 v[62:65], v195, s[48:49] offset:128
	v_pk_mul_f32 v[14:15], v[14:15], v[0:1] op_sel_hi:[1,0]
	v_pk_mul_f32 v[126:127], v[126:127], v[0:1] op_sel_hi:[1,0]
	v_pk_mul_f32 v[116:117], v[116:117], v[0:1] op_sel_hi:[1,0]
	v_pk_mul_f32 v[86:87], v[86:87], v[0:1] op_sel_hi:[1,0]
	v_pk_mul_f32 v[14:15], v[14:15], v[132:133]
	v_pk_mul_f32 v[132:133], v[126:127], v[146:147]
	v_pk_mul_f32 v[126:127], v[116:117], v[134:135]
	v_pk_mul_f32 v[114:115], v[114:115], v[0:1] op_sel_hi:[1,0]
	v_pk_mul_f32 v[112:113], v[112:113], v[0:1] op_sel_hi:[1,0]
	v_pk_mul_f32 v[90:91], v[90:91], v[0:1] op_sel_hi:[1,0]
	v_pk_mul_f32 v[116:117], v[86:87], v[242:243]
	v_lshl_add_u64 v[86:87], s[6:7], 0, v[166:167]
	v_pk_mul_f32 v[134:135], v[114:115], v[136:137]
	v_pk_mul_f32 v[136:137], v[112:113], v[138:139]
	v_pk_mul_f32 v[110:111], v[110:111], v[0:1] op_sel_hi:[1,0]
	v_pk_mul_f32 v[108:109], v[108:109], v[0:1] op_sel_hi:[1,0]
	v_pk_mul_f32 v[106:107], v[106:107], v[0:1] op_sel_hi:[1,0]
	v_pk_mul_f32 v[112:113], v[90:91], v[206:207]
	v_add_co_u32_e32 v90, vcc, s37, v86
	v_pk_mul_f32 v[138:139], v[110:111], v[142:143]
	v_pk_mul_f32 v[142:143], v[108:109], v[144:145]
	v_pk_mul_f32 v[144:145], v[106:107], v[214:215]
	v_pk_mul_f32 v[104:105], v[104:105], v[0:1] op_sel_hi:[1,0]
	v_pk_mul_f32 v[102:103], v[102:103], v[0:1] op_sel_hi:[1,0]
	v_pk_mul_f32 v[92:93], v[92:93], v[0:1] op_sel_hi:[1,0]
	v_pk_mul_f32 v[88:89], v[88:89], v[0:1] op_sel_hi:[1,0]
	v_addc_co_u32_e32 v91, vcc, 0, v87, vcc
	v_lshl_add_u64 v[106:107], s[8:9], 0, v[184:185]
; #define SLOAD(i, t) do { const long rb_ = TROW(t); const char* vt_ = (const char*)Vh + rb_ * (LDK * 2); const char* kt_ = (const char*)Kh + rb_ * (LDK * 2); \
;     sr_[i].vs0 = *(const bf16x8*)(vt_ + lo0); sr_[i].vs1 = *(const bf16x8*)(vt_ + lo0 + 32 * LDK * 2); \
;     sr_[i].ks0 = *(const bf16x8*)(kt_ + lo0); sr_[i].ks1 = *(const bf16x8*)(kt_ + lo0 + 32 * LDK * 2); } while (0)
; #define SWRITE(bb, i) do { *(bf16x8*)((char*)V_lds + (bb) * SHM_V + vst0) = sr_[i].vs0;          \
;     *(bf16x8*)((char*)V_lds + (bb) * SHM_V + vst1) = sr_[i].vs1; int kc = sc * 2;               \
;     *(bf16x8*)((char*)K_lds + (bb) * SHM_K + KSWZ(sr, kc)) = sr_[i].ks0;                       \
;     *(bf16x8*)((char*)K_lds + (bb) * SHM_K + KSWZ(32 + sr, kc)) = sr_[i].ks1; } while (0)
; __device__ __forceinline__ void load_q_roped(const bf16_t* Qw, const float* __restrict__ wq, const float* __restrict__ RT, int pr, int pc, int hi, int lane, bf16x8 (&qr)[8]) {
;     ...
;     for (int lo = 0; lo < 2; ++lo) { const int d0 = hf * 4 + lo;
;       const float* tp = RT + (size_t)((hf ? pc : pr) * 32 + lo * 16 + hi * 8) * 2;
;       f32x4 t[4];
; #pragma unroll
;       for (int q = 0; q < 4; ++q) t[q] = *(const f32x4*)(tp + 4 * q);
; #pragma unroll
;       for (int e = 0; e < 8; ++e) { const float cs = t[e >> 1][(e & 1) * 2], sn = t[e >> 1][(e & 1) * 2 + 1];
;         const float x1 = y[d0][e], x2 = y[d0 + 2][e]; y[d0][e] = x1 * cs - x2 * sn; y[d0 + 2][e] = x1 * sn + x2 * cs; } }
; template <bool META>
; __device__ __forceinline__ void attn_unit(const bf16_t* Q, bf16_t* Oo, const bf16_t* __restrict__ Kb, const bf16_t* __restrict__ Vb, int b, int kvh, int h, int qb, char* lds, const int tid, const float* qn, const float* RT) {
;     ...
;   SLOAD(SE, 0); asm volatile("s_waitcnt vmcnt(0)" ::: "memory"); SWRITE(0, SE); __syncthreads();
	v_pk_mul_f32 v[146:147], v[104:105], v[218:219]
	v_pk_mul_f32 v[148:149], v[102:103], v[226:227]
	v_pk_mul_f32 v[110:111], v[92:93], v[204:205]
	v_pk_mul_f32 v[114:115], v[88:89], v[248:249]
	global_load_dwordx4 v[86:89], v[86:87], off
	s_nop 0
	global_load_dwordx4 v[90:93], v[90:91], off
	v_pk_mul_f32 v[128:129], v[128:129], v[0:1] op_sel_hi:[1,0]
	global_load_dwordx4 v[102:105], v[106:107], off
	v_add_co_u32_e32 v106, vcc, s37, v106
	v_pk_mul_f32 v[120:121], v[120:121], v[0:1] op_sel_hi:[1,0]
	s_nop 0
	v_addc_co_u32_e32 v107, vcc, 0, v107, vcc
	global_load_dwordx4 v[106:109], v[106:107], off
	v_pk_mul_f32 v[2:3], v[2:3], v[0:1] op_sel_hi:[1,0]
	v_pk_mul_f32 v[128:129], v[128:129], v[140:141]
	v_pk_mul_f32 v[140:141], v[120:121], v[220:221]
	v_pk_mul_f32 v[120:121], v[2:3], v[158:159]
	v_pk_mul_f32 v[2:3], v[16:17], v[0:1] op_sel_hi:[1,0]
	v_mov_b32_e32 v17, v48
	v_mov_b32_e32 v48, v47
	v_mov_b32_e32 v16, v46
	v_pk_mul_f32 v[46:47], v[48:49], v[116:117]
	v_pk_mul_f32 v[4:5], v[4:5], v[0:1] op_sel_hi:[1,0]
	v_pk_fma_f32 v[46:47], v[16:17], v[120:121], v[46:47] neg_lo:[0,0,1] neg_hi:[0,0,1]
	v_pk_mul_f32 v[16:17], v[16:17], v[116:117]
	v_pk_mul_f32 v[4:5], v[4:5], v[156:157]
	v_pk_fma_f32 v[16:17], v[48:49], v[120:121], v[16:17]
	v_mov_b32_e32 v49, v44
	v_mov_b32_e32 v44, v43
	v_mov_b32_e32 v48, v42
	v_pk_mul_f32 v[42:43], v[44:45], v[114:115]
	v_pk_mul_f32 v[6:7], v[6:7], v[0:1] op_sel_hi:[1,0]
	v_pk_fma_f32 v[42:43], v[48:49], v[4:5], v[42:43] neg_lo:[0,0,1] neg_hi:[0,0,1]
	v_pk_mul_f32 v[48:49], v[48:49], v[114:115]
	v_pk_mul_f32 v[6:7], v[6:7], v[154:155]
	v_pk_fma_f32 v[114:115], v[44:45], v[4:5], v[48:49]
	v_mov_b32_e32 v5, v40
	v_mov_b32_e32 v40, v39
	v_mov_b32_e32 v4, v38
	v_pk_mul_f32 v[38:39], v[40:41], v[112:113]
	v_pk_mul_f32 v[8:9], v[8:9], v[0:1] op_sel_hi:[1,0]
	v_pk_fma_f32 v[38:39], v[4:5], v[6:7], v[38:39] neg_lo:[0,0,1] neg_hi:[0,0,1]
	v_pk_mul_f32 v[4:5], v[4:5], v[112:113]
	v_pk_mul_f32 v[8:9], v[8:9], v[152:153]
	v_pk_fma_f32 v[112:113], v[40:41], v[6:7], v[4:5]
	v_mov_b32_e32 v5, v32
	v_mov_b32_e32 v32, v31
	v_mov_b32_e32 v4, v30
	v_pk_mul_f32 v[6:7], v[32:33], v[110:111]
	v_pk_mul_f32 v[94:95], v[94:95], v[0:1] op_sel_hi:[1,0]
	v_pk_fma_f32 v[30:31], v[4:5], v[8:9], v[6:7] neg_lo:[0,0,1] neg_hi:[0,0,1]
	v_pk_mul_f32 v[4:5], v[4:5], v[110:111]
	v_pk_mul_f32 v[94:95], v[94:95], v[200:201]
	v_pk_mul_f32 v[10:11], v[10:11], v[0:1] op_sel_hi:[1,0]
	v_pk_fma_f32 v[110:111], v[32:33], v[8:9], v[4:5]
	v_mov_b32_e32 v5, v36
	v_mov_b32_e32 v36, v35
	v_pk_mul_f32 v[10:11], v[10:11], v[150:151]
	v_mov_b32_e32 v4, v34
	v_pk_mul_f32 v[6:7], v[36:37], v[94:95]
	v_pk_mul_f32 v[96:97], v[96:97], v[0:1] op_sel_hi:[1,0]
	v_pk_fma_f32 v[116:117], v[4:5], v[10:11], v[6:7] neg_lo:[0,0,1] neg_hi:[0,0,1]
	v_pk_mul_f32 v[4:5], v[4:5], v[94:95]
	v_pk_mul_f32 v[96:97], v[96:97], v[198:199]
	v_pk_mul_f32 v[12:13], v[12:13], v[0:1] op_sel_hi:[1,0]
	v_pk_fma_f32 v[94:95], v[36:37], v[10:11], v[4:5]
	v_mov_b32_e32 v5, v28
	v_mov_b32_e32 v28, v27
	v_pk_mul_f32 v[12:13], v[12:13], v[202:203]
	v_mov_b32_e32 v4, v26
	v_pk_mul_f32 v[6:7], v[28:29], v[96:97]
	v_pk_mul_f32 v[98:99], v[98:99], v[0:1] op_sel_hi:[1,0]
	v_pk_fma_f32 v[120:121], v[4:5], v[12:13], v[6:7] neg_lo:[0,0,1] neg_hi:[0,0,1]
	v_pk_mul_f32 v[4:5], v[4:5], v[96:97]
	v_pk_mul_f32 v[98:99], v[98:99], v[240:241]
	v_pk_mul_f32 v[82:83], v[82:83], v[0:1] op_sel_hi:[1,0]
	v_pk_fma_f32 v[12:13], v[28:29], v[12:13], v[4:5]
	v_mov_b32_e32 v5, v24
	v_mov_b32_e32 v24, v23
	v_pk_mul_f32 v[82:83], v[82:83], v[238:239]
	v_mov_b32_e32 v4, v22
	v_pk_mul_f32 v[6:7], v[24:25], v[98:99]
	v_pk_mul_f32 v[100:101], v[100:101], v[0:1] op_sel_hi:[1,0]
	v_pk_fma_f32 v[96:97], v[4:5], v[82:83], v[6:7] neg_lo:[0,0,1] neg_hi:[0,0,1]
	v_pk_mul_f32 v[4:5], v[4:5], v[98:99]
	v_pk_mul_f32 v[124:125], v[124:125], v[0:1] op_sel_hi:[1,0]
	v_pk_mul_f32 v[122:123], v[122:123], v[0:1] op_sel_hi:[1,0]
	v_pk_mul_f32 v[118:119], v[118:119], v[0:1] op_sel_hi:[1,0]
	v_pk_mul_f32 v[100:101], v[100:101], v[232:233]
	v_pk_mul_f32 v[84:85], v[84:85], v[0:1] op_sel_hi:[1,0]
	v_pk_fma_f32 v[82:83], v[24:25], v[82:83], v[4:5]
	v_mov_b32_e32 v5, v20
	v_mov_b32_e32 v20, v19
	v_add_u32_e32 v0, 0, v179
	v_pk_mul_f32 v[84:85], v[84:85], v[230:231]
	v_mov_b32_e32 v4, v18
	v_pk_mul_f32 v[6:7], v[20:21], v[100:101]
	s_waitcnt vmcnt(0)
	s_waitcnt vmcnt(3)
	ds_write_b128 v168, v[86:89]
	s_waitcnt vmcnt(2)
	ds_write_b128 v169, v[90:93]
	s_waitcnt vmcnt(1)
	ds_write_b128 v0, v[102:105] offset:49152
	v_add_u32_e32 v0, 0, v180
	v_pk_mul_f32 v[2:3], v[2:3], v[130:131]
	v_pk_fma_f32 v[130:131], v[4:5], v[84:85], v[6:7] neg_lo:[0,0,1] neg_hi:[0,0,1]
	v_pk_mul_f32 v[4:5], v[4:5], v[100:101]
	s_waitcnt vmcnt(0)
	ds_write_b128 v0, v[106:109] offset:49152
	v_add_u32_e32 v0, 0, v182
	v_pk_fma_f32 v[84:85], v[20:21], v[84:85], v[4:5]
	s_waitcnt lgkmcnt(0)
	s_barrier
; __device__ __forceinline__ unsigned cvtpk(float lo, float hi) { const f32x2c v = {lo, hi}; const bf16x2c r = __builtin_convertvector(v, bf16x2c); return __builtin_bit_cast(unsigned, r); }
; __device__ __forceinline__ void qkt(f32x16& p0, f32x16& p1, const bf16_t* Ks, const bf16x8* qr, int r32, int hi) {
;   p0 = f32x16{}; p1 = f32x16{};
; #pragma unroll
;   for (int d0 = 0; d0 < 8; ++d0) { int cb = (d0 * 16 + hi * 8) * 2;
;     bf16x8 b0 = *reinterpret_cast<const bf16x8*>((const char*)Ks + KSWZ(r32, cb));
;     bf16x8 b1 = *reinterpret_cast<const bf16x8*>((const char*)Ks + KSWZ(32 + r32, cb));
;     p0 = __builtin_amdgcn_mfma_f32_32x32x16_bf16(b0, qr[d0], p0, 0, 0, 0);
;     p1 = __builtin_amdgcn_mfma_f32_32x32x16_bf16(b1, qr[d0], p1, 0, 0, 0); }
; }
; __device__ __forceinline__ void load_q_roped(const bf16_t* Qw, const float* __restrict__ wq, const float* __restrict__ RT, int pr, int pc, int hi, int lane, bf16x8 (&qr)[8]) {
;     ...
; #pragma unroll
;   for (int d0 = 0; d0 < 8; ++d0) { u32x4 w; w.x = cvtpk(y[d0][0], y[d0][1]); w.y = cvtpk(y[d0][2], y[d0][3]); w.z = cvtpk(y[d0][4], y[d0][5]); w.w = cvtpk(y[d0][6], y[d0][7]);
;     qr[d0] = *reinterpret_cast<bf16x8*>(&w); }
	ds_read_b128 v[4:7], v0 offset:49152
	v_pk_mul_f32 v[118:119], v[118:119], v[228:229]
	v_mov_b32_e32 v9, v80
	v_mov_b32_e32 v80, v79
	v_mov_b32_e32 v8, v78
	v_pk_mul_f32 v[10:11], v[80:81], v[118:119]
	v_cvt_pk_bf16_f32 v98, v46, v47
	v_cvt_pk_bf16_f32 v99, v42, v43
	v_cvt_pk_bf16_f32 v100, v38, v39
	v_cvt_pk_bf16_f32 v101, v30, v31
	v_mov_b32_e32 v89, v76
	v_mov_b32_e32 v76, v75
	v_pk_fma_f32 v[78:79], v[8:9], v[148:149], v[10:11] neg_lo:[0,0,1] neg_hi:[0,0,1]
	v_pk_mul_f32 v[86:87], v[8:9], v[118:119]
	ds_read_b128 v[8:11], v0 offset:50176
	s_waitcnt lgkmcnt(1)
	v_mfma_f32_32x32x16_bf16 v[18:33], v[4:7], v[98:101], 0
	v_mov_b32_e32 v88, v74
	v_mul_f32_e64 v4, v76, v140
	v_mul_f32_e64 v5, v77, v141
	v_add_u32_e32 v0, 0, v182
	v_fma_f32 v74, v88, v146, -v4
	v_fma_f32 v75, v89, v147, -v5
	ds_read_b128 v[4:7], v0 offset:51200
	v_pk_mul_f32 v[122:123], v[122:123], v[216:217]
	v_mov_b32_e32 v91, v72
	v_cvt_pk_bf16_f32 v102, v116, v117
	v_cvt_pk_bf16_f32 v103, v120, v121
	v_cvt_pk_bf16_f32 v104, v96, v97
	v_cvt_pk_bf16_f32 v105, v130, v131
	v_mov_b32_e32 v72, v71
	s_waitcnt lgkmcnt(1)
	v_mfma_f32_32x32x16_bf16 v[34:49], v[8:11], v[98:101], 0
	v_mov_b32_e32 v90, v70
	ds_read_b128 v[8:11], v0 offset:52224
	v_add_u32_e32 v0, 0, v182
	v_cvt_pk_bf16_f32 v106, v16, v17
	v_cvt_pk_bf16_f32 v107, v114, v115
	v_cvt_pk_bf16_f32 v108, v112, v113
	v_cvt_pk_bf16_f32 v109, v110, v111
	s_waitcnt lgkmcnt(1)
	v_mfma_f32_32x32x16_bf16 v[18:33], v[4:7], v[102:105], v[18:33]
	v_mul_f32_e64 v4, v72, v122
	v_mul_f32_e64 v5, v73, v123
	v_cvt_pk_bf16_f32 v110, v94, v95
	v_fma_f32 v70, v90, v144, -v4
	v_fma_f32 v71, v91, v145, -v5
	ds_read_b128 v[4:7], v0 offset:53248
	v_cvt_pk_bf16_f32 v111, v12, v13
	v_cvt_pk_bf16_f32 v112, v82, v83
	v_cvt_pk_bf16_f32 v113, v84, v85
	s_waitcnt lgkmcnt(1)
	v_mfma_f32_32x32x16_bf16 v[34:49], v[8:11], v[102:105], v[34:49]
	ds_read_b128 v[8:11], v0 offset:54272
	v_add_u32_e32 v0, 0, v182
	v_mov_b32_e32 v97, v60
	v_mov_b32_e32 v60, v59
	v_mov_b32_e32 v96, v58
	v_pk_mul_f32 v[124:125], v[124:125], v[192:193]
	v_mov_b32_e32 v93, v68
	s_waitcnt lgkmcnt(1)
	v_mfma_f32_32x32x16_bf16 v[18:33], v[4:7], v[106:109], v[18:33]
	ds_read_b128 v[4:7], v0 offset:55296
	v_mov_b32_e32 v68, v67
	v_mov_b32_e32 v92, v66
	v_mul_f32_e64 v66, v68, v124
	v_mul_f32_e64 v67, v69, v125
	v_mov_b32_e32 v59, v56
	v_pk_fma_f32 v[16:17], v[92:93], v[142:143], v[66:67] neg_lo:[0,0,1] neg_hi:[0,0,1]
	v_mov_b32_e32 v56, v55
	s_waitcnt lgkmcnt(1)
	v_mfma_f32_32x32x16_bf16 v[34:49], v[8:11], v[106:109], v[34:49]
	ds_read_b128 v[8:11], v0 offset:56320
	v_add_u32_e32 v0, 0, v182
	v_cvt_pk_bf16_f32 v114, v78, v79
	v_cvt_pk_bf16_f32 v115, v74, v75
	v_cvt_pk_bf16_f32 v116, v70, v71
	v_cvt_pk_bf16_f32 v117, v16, v17
	v_mov_b32_e32 v58, v54
	s_waitcnt lgkmcnt(1)
	v_mfma_f32_32x32x16_bf16 v[18:33], v[4:7], v[110:113], v[18:33]
	v_mul_f32_e64 v4, v60, v128
	v_mul_f32_e64 v5, v61, v129
	v_mov_b32_e32 v67, v64
	v_fma_f32 v12, v96, v136, -v4
	v_fma_f32 v13, v97, v137, -v5
	ds_read_b128 v[4:7], v0 offset:57344
	v_mov_b32_e32 v64, v63
	v_mov_b32_e32 v55, v52
	v_mov_b32_e32 v52, v51
	s_waitcnt lgkmcnt(1)
	v_mfma_f32_32x32x16_bf16 v[34:49], v[8:11], v[110:113], v[34:49]
	ds_read_b128 v[8:11], v0 offset:58368
	v_add_u32_e32 v0, 0, v182
	v_mov_b32_e32 v66, v62
	v_mul_f32_e64 v62, v64, v132
	v_mul_f32_e64 v63, v65, v133
	v_mov_b32_e32 v54, v50
	v_pk_fma_f32 v[62:63], v[66:67], v[138:139], v[62:63] neg_lo:[0,0,1] neg_hi:[0,0,1]
	v_cvt_pk_bf16_f32 v119, v12, v13
	s_waitcnt lgkmcnt(1)
	v_mfma_f32_32x32x16_bf16 v[18:33], v[4:7], v[114:117], v[18:33]
	v_mul_f32_e64 v4, v56, v14
	v_mul_f32_e64 v5, v57, v15
	v_cvt_pk_bf16_f32 v118, v62, v63
	v_fma_f32 v16, v58, v134, -v4
	v_fma_f32 v17, v59, v135, -v5
	ds_read_b128 v[4:7], v0 offset:59392
	v_cvt_pk_bf16_f32 v120, v16, v17
	v_pk_fma_f32 v[12:13], v[80:81], v[148:149], v[86:87]
	v_pk_mul_f32 v[14:15], v[58:59], v[14:15]
	s_waitcnt lgkmcnt(1)
	v_mfma_f32_32x32x16_bf16 v[34:49], v[8:11], v[114:117], v[34:49]
	v_mul_f32_e64 v8, v52, v2
	v_mul_f32_e64 v9, v53, v3
	v_mul_f32_e64 v2, v54, v2
	v_mul_f32_e64 v3, v55, v3
	v_fma_f32 v8, v54, v126, -v8
	v_fma_f32 v9, v55, v127, -v9
	v_pk_fma_f32 v[2:3], v[52:53], v[126:127], v[2:3]
	v_cvt_pk_bf16_f32 v121, v8, v9
	ds_read_b128 v[8:11], v0 offset:60416
	v_add_u32_e32 v0, 0, v182
	s_waitcnt lgkmcnt(1)
	v_mfma_f32_32x32x16_bf16 v[18:33], v[4:7], v[118:121], v[18:33]
	v_mul_f32_e64 v4, v88, v140
	v_mul_f32_e64 v5, v89, v141
	v_mov_b64_e32 v[248:249], v[174:175]
	v_fma_f32 v16, v76, v146, v4
	v_fma_f32 v17, v77, v147, v5
	v_pk_mul_f32 v[4:5], v[90:91], v[122:123]
	v_cvt_pk_bf16_f32 v122, v12, v13
	v_pk_fma_f32 v[50:51], v[72:73], v[144:145], v[4:5]
	ds_read_b128 v[4:7], v0 offset:61440
	s_waitcnt lgkmcnt(1)
	v_mfma_f32_32x32x16_bf16 v[34:49], v[8:11], v[118:121], v[34:49]
	v_mul_f32_e64 v8, v92, v124
	v_mul_f32_e64 v9, v93, v125
	v_cvt_pk_bf16_f32 v123, v16, v17
	v_fma_f32 v8, v68, v142, v8
	v_fma_f32 v9, v69, v143, v9
	v_cvt_pk_bf16_f32 v124, v50, v51
	v_cvt_pk_bf16_f32 v125, v8, v9
	ds_read_b128 v[8:11], v0 offset:62464
	v_add_u32_e32 v0, 0, v182
	s_waitcnt lgkmcnt(1)
	v_mfma_f32_32x32x16_bf16 v[18:33], v[4:7], v[122:125], v[18:33]
	v_mul_f32_e64 v4, v66, v132
	v_mul_f32_e64 v5, v67, v133
	v_mov_b64_e32 v[242:243], v[244:245]
	v_fma_f32 v12, v64, v138, v4
	v_fma_f32 v13, v65, v139, v5
	v_pk_mul_f32 v[4:5], v[96:97], v[128:129]
	v_cvt_pk_bf16_f32 v126, v12, v13
	v_pk_fma_f32 v[16:17], v[60:61], v[136:137], v[4:5]
	ds_read_b128 v[4:7], v0 offset:63488
	s_waitcnt lgkmcnt(1)
; #define SLOAD(i, t) do { const long rb_ = TROW(t); const char* vt_ = (const char*)Vh + rb_ * (LDK * 2); const char* kt_ = (const char*)Kh + rb_ * (LDK * 2); \
;     sr_[i].vs0 = *(const bf16x8*)(vt_ + lo0); sr_[i].vs1 = *(const bf16x8*)(vt_ + lo0 + 32 * LDK * 2); \
;     sr_[i].ks0 = *(const bf16x8*)(kt_ + lo0); sr_[i].ks1 = *(const bf16x8*)(kt_ + lo0 + 32 * LDK * 2); } while (0)
; #define SWRITE(bb, i) do { *(bf16x8*)((char*)V_lds + (bb) * SHM_V + vst0) = sr_[i].vs0;          \
;     *(bf16x8*)((char*)V_lds + (bb) * SHM_V + vst1) = sr_[i].vs1; int kc = sc * 2;               \
;     *(bf16x8*)((char*)K_lds + (bb) * SHM_K + KSWZ(sr, kc)) = sr_[i].ks0;                       \
;     *(bf16x8*)((char*)K_lds + (bb) * SHM_K + KSWZ(32 + sr, kc)) = sr_[i].ks1; } while (0)
; #define SWAIT() asm volatile("s_waitcnt vmcnt(0)" ::: "memory")
; __device__ __forceinline__ void partialSM(f32x16& p0, f32x16& p1, float& m_reg, float& mn, float& alpha) {
;   constexpr float C = ASCALE * 1.4426950408889634f;
;   float pmax = p0[0];
; #pragma unroll
;   for (int r = 1; r < 16; ++r) pmax = fmaxf(pmax, p0[r]);
; #pragma unroll
;   for (int r = 0; r < 16; ++r) pmax = fmaxf(pmax, p1[r]);
;   { auto rr = __builtin_amdgcn_permlane32_swap(__float_as_uint(pmax), __float_as_uint(pmax), false, false);
;     pmax = fmaxf(__uint_as_float(rr[0]), __uint_as_float(rr[1])); }
;   if (__builtin_expect(__all(pmax - m_reg <= ATHR / ASCALE), 1)) { mn = m_reg; alpha = 1.f; }
;   else { mn = fmaxf(m_reg, pmax); alpha = __builtin_amdgcn_exp2f((m_reg - mn) * C); m_reg = mn; }
;   float mnC = -mn * C;
; #pragma unroll
;   for (int r = 0; r < 16; ++r) p0[r] = fmaf(p0[r], C, mnC);
; #pragma unroll
;   for (int r = 0; r < 16; ++r) p1[r] = fmaf(p1[r], C, mnC);
; template <bool META>
; __device__ __forceinline__ void attn_unit(const bf16_t* Q, bf16_t* Oo, const bf16_t* __restrict__ Kb, const bf16_t* __restrict__ Vb, int b, int kvh, int h, int qb, char* lds, const int tid, const float* qn, const float* RT) {
;     ...
;   qkt(pA0, pA1, K_lds, qr, r32, hi); partialSM(pA0, pA1, m_reg, mnA, alA);
;   SLOAD(SO, 1);
;   SWAIT(); SWRITE(1, SO); __syncthreads();
;   int bc = 1;
	v_mfma_f32_32x32x16_bf16 v[34:49], v[8:11], v[122:125], v[34:49]
	v_fma_f32 v8, v56, v134, v14
	v_fma_f32 v9, v57, v135, v15
	v_cvt_pk_bf16_f32 v127, v16, v17
	v_cvt_pk_bf16_f32 v128, v8, v9
	v_cvt_pk_bf16_f32 v129, v2, v3
	ds_read_b128 v[8:11], v0 offset:64512
	v_mov_b32_e32 v245, v196
	s_waitcnt lgkmcnt(1)
	v_mfma_f32_32x32x16_bf16 v[18:33], v[4:7], v[126:129], v[18:33]
	s_waitcnt lgkmcnt(0)
	v_mfma_f32_32x32x16_bf16 v[34:49], v[8:11], v[126:129], v[34:49]
	s_nop 9
	v_max_f32_e32 v0, v19, v19
	v_max_f32_e32 v2, v18, v18
	v_max_f32_e32 v0, v2, v0
	v_max3_f32 v0, v0, v20, v21
	v_max3_f32 v0, v0, v22, v23
	v_max3_f32 v0, v0, v24, v25
	v_max3_f32 v0, v0, v26, v27
	v_max3_f32 v0, v0, v28, v29
	v_max3_f32 v0, v0, v30, v31
	v_max3_f32 v0, v0, v32, v33
	v_max3_f32 v0, v0, v34, v35
	v_max3_f32 v0, v0, v36, v37
	v_max3_f32 v0, v0, v38, v39
	v_max3_f32 v0, v0, v40, v41
	v_max3_f32 v0, v0, v42, v43
	v_max3_f32 v0, v0, v44, v45
	v_max3_f32 v0, v0, v46, v47
	v_max3_f32 v0, v0, v48, v49
	v_mov_b32_e32 v2, v0
	s_nop 1
	v_permlane32_swap_b32_e32 v0, v2
	v_max_f32_e32 v2, v2, v2
	v_max_f32_e32 v0, v0, v0
	v_max_f32_e32 v0, v0, v2
	v_add_f32_e32 v2, 0x7149f2ca, v0
	v_cmp_ge_f32_e32 vcc, s25, v2
	s_cmp_eq_u64 vcc, exec
	s_cselect_b64 vcc, -1, 0
	s_bitset1_b32 s0, 15
	s_add_u32 s6, s42, s0
	s_addc_u32 s7, s43, s1
	s_add_u32 s8, s40, s0
	v_lshl_add_u64 v[2:3], s[6:7], 0, v[166:167]
	s_addc_u32 s9, s41, s1
	v_add_co_u32_e64 v4, s[0:1], s37, v2
	v_max_f32_e32 v0, 0xf149f2ca, v0
	s_nop 0
	v_addc_co_u32_e64 v5, s[0:1], 0, v3, s[0:1]
	global_load_dwordx4 v[50:53], v[2:3], off
	global_load_dwordx4 v[54:57], v[4:5], off
	v_lshl_add_u64 v[2:3], s[8:9], 0, v[184:185]
	global_load_dwordx4 v[58:61], v[2:3], off
	v_add_co_u32_e64 v2, s[0:1], s37, v2
	v_cndmask_b32_e32 v150, v0, v246, vcc
	s_nop 0
	v_addc_co_u32_e64 v3, s[0:1], 0, v3, s[0:1]
	global_load_dwordx4 v[62:65], v[2:3], off
	v_sub_f32_e32 v2, 0xf149f2ca, v0
	v_mul_f32_e32 v2, 0x3e0293ee, v2
	v_exp_f32_e32 v66, v2
	v_mul_f32_e32 v0, 0xbe0293ee, v150
	v_fmamk_f32 v18, v18, 0x3e0293ee, v0
	v_fmamk_f32 v19, v19, 0x3e0293ee, v0
	v_cndmask_b32_e64 v192, v66, 1.0, vcc
	v_mov_b32_e32 v66, v0
	v_fmamk_f32 v20, v20, 0x3e0293ee, v0
	v_fmamk_f32 v21, v21, 0x3e0293ee, v0
	v_fmamk_f32 v22, v22, 0x3e0293ee, v0
	v_fmamk_f32 v23, v23, 0x3e0293ee, v0
	v_fmamk_f32 v24, v24, 0x3e0293ee, v0
	v_fmamk_f32 v25, v25, 0x3e0293ee, v0
	v_fmamk_f32 v26, v26, 0x3e0293ee, v0
	v_fmamk_f32 v27, v27, 0x3e0293ee, v0
	v_fmamk_f32 v28, v28, 0x3e0293ee, v0
	v_fmamk_f32 v29, v29, 0x3e0293ee, v0
	v_fmamk_f32 v30, v30, 0x3e0293ee, v0
	v_fmamk_f32 v31, v31, 0x3e0293ee, v0
	v_fmamk_f32 v32, v32, 0x3e0293ee, v0
	v_fmac_f32_e32 v66, 0x3e0293ee, v33
	s_add_i32 s0, 0, 0x10000
	s_mov_b32 s6, s5
	s_mov_b32 s7, s5
	s_mov_b32 s8, s5
	s_mov_b32 s9, s5
	v_mov_b64_e32 v[2:3], s[4:5]
	v_pk_fma_f32 v[130:131], v[48:49], s[36:37], v[0:1] op_sel_hi:[1,0,0]
	v_pk_fma_f32 v[132:133], v[46:47], s[36:37], v[0:1] op_sel_hi:[1,0,0]
	v_pk_fma_f32 v[134:135], v[44:45], s[36:37], v[0:1] op_sel_hi:[1,0,0]
	v_pk_fma_f32 v[136:137], v[42:43], s[36:37], v[0:1] op_sel_hi:[1,0,0]
	v_pk_fma_f32 v[138:139], v[40:41], s[36:37], v[0:1] op_sel_hi:[1,0,0]
	v_pk_fma_f32 v[140:141], v[38:39], s[36:37], v[0:1] op_sel_hi:[1,0,0]
	v_pk_fma_f32 v[142:143], v[36:37], s[36:37], v[0:1] op_sel_hi:[1,0,0]
	v_pk_fma_f32 v[144:145], v[34:35], s[36:37], v[0:1] op_sel_hi:[1,0,0]
	v_exp_f32_e32 v146, v18
	v_exp_f32_e32 v147, v19
	v_exp_f32_e32 v148, v20
	v_exp_f32_e32 v159, v21
	v_exp_f32_e32 v160, v22
	v_exp_f32_e32 v209, v23
	v_exp_f32_e32 v149, v24
	v_exp_f32_e32 v161, v25
	v_exp_f32_e32 v151, v26
	v_exp_f32_e32 v153, v27
	v_exp_f32_e32 v154, v28
	v_exp_f32_e32 v157, v29
	v_exp_f32_e32 v152, v30
	v_exp_f32_e32 v155, v31
	v_exp_f32_e32 v156, v32
	v_exp_f32_e32 v158, v66
	v_add_u32_e32 v0, s0, v179
	v_mov_b64_e32 v[16:17], s[18:19]
	s_waitcnt vmcnt(0)
	s_waitcnt vmcnt(3)
	ds_write_b128 v168, v[50:53] offset:16384
	s_waitcnt vmcnt(2)
	ds_write_b128 v169, v[54:57] offset:16384
	v_mov_b64_e32 v[4:5], s[6:7]
	s_waitcnt vmcnt(1)
	ds_write_b128 v0, v[58:61]
	v_add_u32_e32 v0, s0, v180
	v_mov_b64_e32 v[6:7], s[8:9]
	v_mov_b64_e32 v[8:9], s[10:11]
	v_mov_b64_e32 v[10:11], s[12:13]
	v_mov_b64_e32 v[12:13], s[14:15]
	v_mov_b64_e32 v[14:15], s[16:17]
	s_waitcnt vmcnt(0)
	ds_write_b128 v0, v[62:65]
	v_mov_b64_e32 v[64:65], v[16:17]
	v_mov_b64_e32 v[48:49], v[16:17]
	v_mov_b64_e32 v[32:33], v[16:17]
	v_lshl_add_u64 v[168:169], s[42:43], 0, v[166:167]
	s_mov_b64 s[12:13], s[42:43]
	s_mov_b64 s[14:15], s[40:41]
	v_lshrrev_b32_e32 v239, 6, v208
	s_nop 0
	v_readfirstlane_b32 s18, v239
	s_lshl_b32 s18, s18, 11
	v_add_u32_e32 v238, 0x4000, v166
	s_bitset1_b32 s90, 7
	v_mov_b32_e32 v0, 0
	s_mov_b32 s4, -1
	v_mov_b64_e32 v[62:63], v[14:15]
	v_mov_b64_e32 v[60:61], v[12:13]
	v_mov_b64_e32 v[58:59], v[10:11]
	v_mov_b64_e32 v[56:57], v[8:9]
	v_mov_b64_e32 v[54:55], v[6:7]
	v_mov_b64_e32 v[52:53], v[4:5]
	v_mov_b64_e32 v[50:51], v[2:3]
	v_mov_b64_e32 v[46:47], v[14:15]
	v_mov_b64_e32 v[44:45], v[12:13]
	v_mov_b64_e32 v[42:43], v[10:11]
	v_mov_b64_e32 v[40:41], v[8:9]
	v_mov_b64_e32 v[38:39], v[6:7]
	v_mov_b64_e32 v[36:37], v[4:5]
	v_mov_b64_e32 v[34:35], v[2:3]
	v_mov_b64_e32 v[30:31], v[14:15]
	v_mov_b64_e32 v[28:29], v[12:13]
	v_mov_b64_e32 v[26:27], v[10:11]
	v_mov_b64_e32 v[24:25], v[8:9]
	v_mov_b64_e32 v[22:23], v[6:7]
	v_mov_b64_e32 v[20:21], v[4:5]
	v_mov_b64_e32 v[18:19], v[2:3]
	s_mov_b32 s6, s28
	v_sub_co_u32_e64 v66, s[0:1], s6, 1
	s_and_b64 s[0:1], s[0:1], exec
	v_readfirstlane_b32 s0, v66
	s_cselect_b32 s28, 2, s0
	s_lshl_b32 s9, s6, 14
	s_add_i32 s0, s9, 0
	v_add_u32_e32 v195, s0, v182
	s_waitcnt lgkmcnt(0)
	s_barrier
; #define SBAR() __builtin_amdgcn_sched_barrier(0)
; #define SLOAD(i, t) do { const long rb_ = TROW(t); const char* vt_ = (const char*)Vh + rb_ * (LDK * 2); const char* kt_ = (const char*)Kh + rb_ * (LDK * 2); \
;     sr_[i].vs0 = *(const bf16x8*)(vt_ + lo0); sr_[i].vs1 = *(const bf16x8*)(vt_ + lo0 + 32 * LDK * 2); \
;     sr_[i].ks0 = *(const bf16x8*)(kt_ + lo0); sr_[i].ks1 = *(const bf16x8*)(kt_ + lo0 + 32 * LDK * 2); } while (0)
; __device__ __forceinline__ void finishSM(f32x16& p0, f32x16& p1, float alpha, float& l_reg, bf16x8& pa0, bf16x8& pa1, bf16x8& pa2, bf16x8& pa3) {
; #pragma unroll
;   for (int r = 0; r < 16; ++r) p1[r] = __builtin_amdgcn_exp2f(p1[r]);
;   float ps = 0;
; #pragma unroll
;   for (int r = 0; r < 16; ++r) ps += p0[r];
; #pragma unroll
;   for (int r = 0; r < 16; ++r) ps += p1[r];
;   { auto rr = __builtin_amdgcn_permlane32_swap(__float_as_uint(ps), __float_as_uint(ps), false, false);
;     ps = __uint_as_float(rr[0]) + __uint_as_float(rr[1]); }
;   l_reg = l_reg * alpha + ps;
;     ...
;   PK4(p0, 0, pa0); PK4(p0, 8, pa1); PK4(p1, 0, pa2); PK4(p1, 8, pa3);
; template <bool META>
; __device__ __forceinline__ void attn_unit(const bf16_t* Q, bf16_t* Oo, const bf16_t* __restrict__ Kb, const bf16_t* __restrict__ Vb, int b, int kvh, int h, int qb, char* lds, const int tid, const float* qn, const float* RT) {
;     ...
;   for (int j = 1; j + 1 < NT; j += 2) {
;     const int bn = bc == 2 ? 0 : bc + 1, bp = bc == 0 ? 2 : bc - 1;
;     SBAR(); qkt(pB0, pB1, (bf16_t*)((char*)K_lds + bc * SHM_K), qr, r32, hi);
;     finishSM(pA0, pA1, alA, l_reg, pa0, pa1, pa2, pa3); SBAR();
;     SLOAD(SO, j + 1);
.LBB0_260:
	ds_read_b128 v[66:69], v195 offset:49152
	ds_read_b128 v[70:73], v195 offset:50176
	ds_read_b128 v[210:213], v195 offset:51200
	ds_read_b128 v[214:217], v195 offset:52224
	s_waitcnt lgkmcnt(3)
	v_mfma_f32_32x32x16_bf16 v[82:97], v[66:69], v[98:101], 0
	v_exp_f32_e32 v144, v144
	v_exp_f32_e32 v145, v145
	v_exp_f32_e32 v142, v142
	v_exp_f32_e32 v143, v143
	v_exp_f32_e32 v140, v140
	v_exp_f32_e32 v141, v141
	v_exp_f32_e32 v138, v138
	s_waitcnt lgkmcnt(2)
	v_mfma_f32_32x32x16_bf16 v[66:81], v[70:73], v[98:101], 0
	v_exp_f32_e32 v139, v139
	v_exp_f32_e32 v136, v136
	v_exp_f32_e32 v137, v137
	v_exp_f32_e32 v134, v134
	v_exp_f32_e32 v135, v135
	v_exp_f32_e32 v132, v132
	v_exp_f32_e32 v133, v133
	s_waitcnt lgkmcnt(1)
	v_mfma_f32_32x32x16_bf16 v[82:97], v[210:213], v[102:105], v[82:97]
	v_exp_f32_e32 v130, v130
	v_exp_f32_e32 v131, v131
	s_waitcnt lgkmcnt(0)
	v_mfma_f32_32x32x16_bf16 v[66:81], v[214:217], v[102:105], v[66:81]
	ds_read_b128 v[210:213], v195 offset:53248
	ds_read_b128 v[214:217], v195 offset:54272
	s_waitcnt lgkmcnt(1)
	v_mfma_f32_32x32x16_bf16 v[82:97], v[210:213], v[106:109], v[82:97]
	s_waitcnt lgkmcnt(0)
	v_mfma_f32_32x32x16_bf16 v[66:81], v[214:217], v[106:109], v[66:81]
	ds_read_b128 v[210:213], v195 offset:55296
	ds_read_b128 v[214:217], v195 offset:56320
	s_waitcnt lgkmcnt(1)
	v_mfma_f32_32x32x16_bf16 v[82:97], v[210:213], v[110:113], v[82:97]
	s_waitcnt lgkmcnt(0)
	v_mfma_f32_32x32x16_bf16 v[66:81], v[214:217], v[110:113], v[66:81]
	ds_read_b128 v[210:213], v195 offset:57344
	ds_read_b128 v[214:217], v195 offset:58368
	s_waitcnt lgkmcnt(1)
	v_mfma_f32_32x32x16_bf16 v[82:97], v[210:213], v[114:117], v[82:97]
	s_waitcnt lgkmcnt(0)
	v_mfma_f32_32x32x16_bf16 v[66:81], v[214:217], v[114:117], v[66:81]
	ds_read_b128 v[210:213], v195 offset:59392
	ds_read_b128 v[214:217], v195 offset:60416
	s_waitcnt lgkmcnt(1)
	v_mfma_f32_32x32x16_bf16 v[82:97], v[210:213], v[118:121], v[82:97]
	s_waitcnt lgkmcnt(0)
	v_mfma_f32_32x32x16_bf16 v[66:81], v[214:217], v[118:121], v[66:81]
	ds_read_b128 v[210:213], v195 offset:61440
	ds_read_b128 v[214:217], v195 offset:62464
	s_waitcnt lgkmcnt(1)
	v_mfma_f32_32x32x16_bf16 v[82:97], v[210:213], v[122:125], v[82:97]
	s_waitcnt lgkmcnt(0)
	v_mfma_f32_32x32x16_bf16 v[66:81], v[214:217], v[122:125], v[66:81]
	ds_read_b128 v[210:213], v195 offset:63488
	ds_read_b128 v[214:217], v195 offset:64512
	v_add_f32_e32 v193, v147, v146
	v_add_f32_e32 v193, v148, v193
	v_add_f32_e32 v193, v159, v193
	v_add_f32_e32 v193, v160, v193
	v_add_f32_e32 v193, v209, v193
	v_add_f32_e32 v193, v149, v193
	v_add_f32_e32 v193, v161, v193
	v_add_f32_e32 v193, v151, v193
	v_add_f32_e32 v193, v153, v193
	v_add_f32_e32 v193, v154, v193
	v_add_f32_e32 v193, v157, v193
	v_add_f32_e32 v193, v152, v193
	v_add_f32_e32 v193, v155, v193
	v_add_f32_e32 v193, v156, v193
	v_add_f32_e32 v193, v158, v193
	v_add_f32_e32 v193, v144, v193
	v_add_f32_e32 v193, v145, v193
	v_add_f32_e32 v193, v142, v193
	v_add_f32_e32 v193, v143, v193
	v_add_f32_e32 v193, v140, v193
	v_add_f32_e32 v193, v141, v193
	v_add_f32_e32 v193, v138, v193
	v_add_f32_e32 v193, v139, v193
	v_add_f32_e32 v193, v136, v193
	v_add_f32_e32 v193, v137, v193
	s_waitcnt lgkmcnt(1)
	v_mfma_f32_32x32x16_bf16 v[82:97], v[210:213], v[126:129], v[82:97]
	v_add_f32_e32 v193, v134, v193
	v_add_f32_e32 v193, v135, v193
	v_add_f32_e32 v193, v132, v193
	v_add_f32_e32 v193, v133, v193
	v_add_f32_e32 v193, v130, v193
	v_add_f32_e32 v193, v131, v193
	v_mov_b32_e32 v195, v193
	s_waitcnt lgkmcnt(0)
	v_mfma_f32_32x32x16_bf16 v[66:81], v[214:217], v[126:129], v[66:81]
	v_cvt_pk_bf16_f32 v146, v146, v147
	v_cvt_pk_bf16_f32 v147, v148, v159
	v_cvt_pk_bf16_f32 v148, v160, v209
	v_permlane32_swap_b32_e32 v193, v195
	v_cvt_pk_bf16_f32 v149, v149, v161
	v_permlane32_swap_b32_e32 v146, v148
	v_cvt_pk_bf16_f32 v210, v151, v153
	v_cvt_pk_bf16_f32 v211, v154, v157
	v_cvt_pk_bf16_f32 v212, v152, v155
	v_cvt_pk_bf16_f32 v213, v156, v158
	v_cvt_pk_bf16_f32 v152, v144, v145
	v_cvt_pk_bf16_f32 v153, v142, v143
	v_cvt_pk_bf16_f32 v154, v140, v141
	v_cvt_pk_bf16_f32 v155, v138, v139
	v_cvt_pk_bf16_f32 v156, v136, v137
	v_cvt_pk_bf16_f32 v157, v134, v135
	v_cvt_pk_bf16_f32 v158, v132, v133
	v_cvt_pk_bf16_f32 v159, v130, v131
	v_permlane32_swap_b32_e32 v147, v149
	v_permlane32_swap_b32_e32 v210, v212
	v_permlane32_swap_b32_e32 v211, v213
	v_permlane32_swap_b32_e32 v152, v154
	v_permlane32_swap_b32_e32 v153, v155
	v_permlane32_swap_b32_e32 v156, v158
	v_permlane32_swap_b32_e32 v157, v159
	s_lshl_b32 s8, s28, 14
	v_add_u32_e32 v151, s8, v178
	ds_read_b64_tr_b16 v[214:215], v151 offset:0
	ds_read_b64_tr_b16 v[216:217], v151 offset:0x800
	ds_read_b64_tr_b16 v[218:219], v151 offset:0x1000
	ds_read_b64_tr_b16 v[220:221], v151 offset:0x1800
	ds_read_b64_tr_b16 v[222:223], v151 offset:0x2000
	ds_read_b64_tr_b16 v[224:225], v151 offset:0x2800
	ds_read_b64_tr_b16 v[226:227], v151 offset:0x3000
	ds_read_b64_tr_b16 v[228:229], v151 offset:0x3800
	s_cmpk_lg_i32 s4, 0xfd
	s_cselect_b64 s[0:1], -1, 0
	s_cmpk_eq_i32 s4, 0xfd
	s_cselect_b64 s[40:41], -1, 0
	s_and_b64 s[10:11], s[40:41], exec
	s_cselect_b32 s11, s44, s91
	s_cselect_b32 s10, s31, s90
	s_lshl_b64 s[10:11], s[10:11], 9
	s_add_i32 s19, s9, 0x4000
	s_cmp_lg_u32 s6, 2
	s_cselect_b32 s19, s19, 0
	s_add_i32 s19, s19, s18
	s_add_u32 s16, s12, s10
	s_addc_u32 s17, s13, s11
	s_mov_b32 m0, s19
	s_nop 0
	global_load_lds_dwordx4 v187, s[16:17]
	s_add_i32 m0, s19, 0x380
	s_nop 0
	global_load_lds_dwordx4 v187, s[16:17] offset:128
	s_add_u32 s16, s14, s10
	s_addc_u32 s17, s15, s11
	s_add_i32 m0, s19, 0xc000
	s_nop 0
	global_load_lds_dwordx4 v188, s[16:17]
	s_add_u32 s16, s16, 0x4000
	s_addc_u32 s17, s17, 0
	s_add_i32 m0, s19, 0xc400
	s_nop 0
	global_load_lds_dwordx4 v188, s[16:17]
	s_waitcnt lgkmcnt(6)
; #define SBAR() __builtin_amdgcn_sched_barrier(0)
; __device__ __forceinline__ void partialSM(f32x16& p0, f32x16& p1, float& m_reg, float& mn, float& alpha) {
;   constexpr float C = ASCALE * 1.4426950408889634f;
;   float pmax = p0[0];
; #pragma unroll
;   for (int r = 1; r < 16; ++r) pmax = fmaxf(pmax, p0[r]);
; #pragma unroll
;   for (int r = 0; r < 16; ++r) pmax = fmaxf(pmax, p1[r]);
;   { auto rr = __builtin_amdgcn_permlane32_swap(__float_as_uint(pmax), __float_as_uint(pmax), false, false);
;     pmax = fmaxf(__uint_as_float(rr[0]), __uint_as_float(rr[1])); }
;   if (__builtin_expect(__all(pmax - m_reg <= ATHR / ASCALE), 1)) { mn = m_reg; alpha = 1.f; }
;   else { mn = fmaxf(m_reg, pmax); alpha = __builtin_amdgcn_exp2f((m_reg - mn) * C); m_reg = mn; }
; template <int D0> __device__ __forceinline__ void pv_one(f32x16& od, int vb, bf16x8 pa0, bf16x8 pa1, bf16x8 pa2, bf16x8 pa3) {
;   const s16x4 l0 = tr_read<v_rd_off(D0, 0, 0)>(vb), h0 = tr_read<v_rd_off(D0, 0, 1)>(vb), l1 = tr_read<v_rd_off(D0, 1, 0)>(vb), h1 = tr_read<v_rd_off(D0, 1, 1)>(vb);
;   const s16x4 l2 = tr_read<v_rd_off(D0, 2, 0)>(vb), h2 = tr_read<v_rd_off(D0, 2, 1)>(vb), l3 = tr_read<v_rd_off(D0, 3, 0)>(vb), h3 = tr_read<v_rd_off(D0, 3, 1)>(vb);
;   asm volatile("s_waitcnt lgkmcnt(0)" ::: "memory"); SBAR();
;     ...
;   od = __builtin_amdgcn_mfma_f32_32x32x16_bf16(pa0, PK(l0, h0), od, 0, 0, 0);
;   od = __builtin_amdgcn_mfma_f32_32x32x16_bf16(pa1, PK(l1, h1), od, 0, 0, 0);
;   od = __builtin_amdgcn_mfma_f32_32x32x16_bf16(pa2, PK(l2, h2), od, 0, 0, 0);
;   od = __builtin_amdgcn_mfma_f32_32x32x16_bf16(pa3, PK(l3, h3), od, 0, 0, 0);
;     ...
; }
; __device__ __forceinline__ void pv_d0(f32x16* o, int vb, bf16x8 pa0, bf16x8 pa1, bf16x8 pa2, bf16x8 pa3) {
;   pv_one<0>(o[0], vb, pa0, pa1, pa2, pa3); pv_one<1>(o[1], vb, pa0, pa1, pa2, pa3); pv_one<2>(o[2], vb, pa0, pa1, pa2, pa3); pv_one<3>(o[3], vb, pa0, pa1, pa2, pa3);
	s_nop 0
	v_mfma_f32_32x32x16_bf16 v[2:17], v[146:149], v[214:217], v[2:17]
	ds_read_b64_tr_b16 v[214:215], v151 offset:0x200
	ds_read_b64_tr_b16 v[216:217], v151 offset:0xa00
	s_waitcnt lgkmcnt(6)
	v_mfma_f32_32x32x16_bf16 v[2:17], v[210:213], v[218:221], v[2:17]
	ds_read_b64_tr_b16 v[218:219], v151 offset:0x1200
	ds_read_b64_tr_b16 v[220:221], v151 offset:0x1a00
	s_waitcnt lgkmcnt(6)
	v_mfma_f32_32x32x16_bf16 v[2:17], v[152:155], v[222:225], v[2:17]
	ds_read_b64_tr_b16 v[222:223], v151 offset:0x2200
	ds_read_b64_tr_b16 v[224:225], v151 offset:0x2a00
	s_waitcnt lgkmcnt(6)
	v_mfma_f32_32x32x16_bf16 v[2:17], v[156:159], v[226:229], v[2:17]
	ds_read_b64_tr_b16 v[226:227], v151 offset:0x3200
	ds_read_b64_tr_b16 v[228:229], v151 offset:0x3a00
	s_waitcnt lgkmcnt(6)
	v_mfma_f32_32x32x16_bf16 v[50:65], v[146:149], v[214:217], v[50:65]
	ds_read_b64_tr_b16 v[214:215], v151 offset:0x400
	ds_read_b64_tr_b16 v[216:217], v151 offset:0xc00
	s_waitcnt lgkmcnt(6)
	v_mfma_f32_32x32x16_bf16 v[50:65], v[210:213], v[218:221], v[50:65]
	ds_read_b64_tr_b16 v[218:219], v151 offset:0x1400
	ds_read_b64_tr_b16 v[220:221], v151 offset:0x1c00
	s_waitcnt lgkmcnt(6)
	v_mfma_f32_32x32x16_bf16 v[50:65], v[152:155], v[222:225], v[50:65]
	ds_read_b64_tr_b16 v[222:223], v151 offset:0x2400
	ds_read_b64_tr_b16 v[224:225], v151 offset:0x2c00
	s_waitcnt lgkmcnt(6)
	v_mfma_f32_32x32x16_bf16 v[50:65], v[156:159], v[226:229], v[50:65]
	ds_read_b64_tr_b16 v[226:227], v151 offset:0x3400
	ds_read_b64_tr_b16 v[228:229], v151 offset:0x3c00
	s_waitcnt lgkmcnt(6)
	v_mfma_f32_32x32x16_bf16 v[34:49], v[146:149], v[214:217], v[34:49]
	ds_read_b64_tr_b16 v[214:215], v151 offset:0x600
	ds_read_b64_tr_b16 v[216:217], v151 offset:0xe00
	s_waitcnt lgkmcnt(6)
	v_mfma_f32_32x32x16_bf16 v[34:49], v[210:213], v[218:221], v[34:49]
	ds_read_b64_tr_b16 v[218:219], v151 offset:0x1600
	ds_read_b64_tr_b16 v[220:221], v151 offset:0x1e00
	s_waitcnt lgkmcnt(6)
	v_mfma_f32_32x32x16_bf16 v[34:49], v[152:155], v[222:225], v[34:49]
	ds_read_b64_tr_b16 v[222:223], v151 offset:0x2600
	ds_read_b64_tr_b16 v[224:225], v151 offset:0x2e00
	s_waitcnt lgkmcnt(6)
	v_mfma_f32_32x32x16_bf16 v[34:49], v[156:159], v[226:229], v[34:49]
	ds_read_b64_tr_b16 v[226:227], v151 offset:0x3600
	ds_read_b64_tr_b16 v[228:229], v151 offset:0x3e00
	s_waitcnt lgkmcnt(6)
	v_mfma_f32_32x32x16_bf16 v[18:33], v[146:149], v[214:217], v[18:33]
	v_max_f32_e32 v146, v82, v83
	v_max3_f32 v146, v146, v84, v85
	v_max3_f32 v146, v146, v86, v87
	v_max3_f32 v146, v146, v88, v89
	v_max3_f32 v146, v146, v90, v91
	v_max3_f32 v146, v146, v92, v93
	v_max3_f32 v146, v146, v94, v95
	v_max3_f32 v146, v146, v96, v97
	v_max3_f32 v146, v146, v66, v67
	s_waitcnt lgkmcnt(4)
	v_mfma_f32_32x32x16_bf16 v[18:33], v[210:213], v[218:221], v[18:33]
	v_max3_f32 v146, v146, v68, v69
	v_max3_f32 v146, v146, v70, v71
	v_max3_f32 v146, v146, v72, v73
	v_max3_f32 v146, v146, v74, v75
	v_max3_f32 v146, v146, v76, v77
	v_max3_f32 v146, v146, v78, v79
	v_max3_f32 v146, v146, v80, v81
	v_mov_b32_e32 v147, v146
	s_waitcnt lgkmcnt(2)
	v_mfma_f32_32x32x16_bf16 v[18:33], v[152:155], v[222:225], v[18:33]
	s_nop 0
	v_permlane32_swap_b32_e32 v146, v147
	v_max_f32_e32 v146, v146, v147
	v_sub_f32_e32 v147, v146, v150
	v_cmp_ge_f32_e32 vcc, s25, v147
	v_max_f32_e32 v146, v150, v146
	v_sub_f32_e32 v147, v150, v146
	s_cmp_eq_u64 vcc, exec
	v_mul_f32_e32 v147, 0x3e0293ee, v147
	s_waitcnt lgkmcnt(0)
	v_mfma_f32_32x32x16_bf16 v[18:33], v[156:159], v[226:229], v[18:33]
	s_cselect_b64 s[42:43], -1, 0
	v_exp_f32_e32 v147, v147
	s_add_i32 s7, s9, 0x4000
	s_cmp_lg_u32 s6, 2
	s_cselect_b32 s6, s7, 0
	s_add_i32 s10, s6, 0
	v_cndmask_b32_e64 v196, v147, 1.0, s[42:43]
	v_cmp_gt_f32_e32 vcc, 1.0, v196
	s_cbranch_vccz .LBB0_264
	s_and_saveexec_b64 s[6:7], s[38:39]
	ds_write_b32 v190, v196 offset:128
	s_or_b64 exec, exec, s[6:7]
	s_waitcnt lgkmcnt(0)
	v_add_u32_e32 v147, v173, v181
	ds_read_b128 v[152:155], v147 offset:224
	ds_read_b128 v[156:159], v147 offset:192
	ds_read_b128 v[210:213], v147 offset:160
	ds_read_b128 v[214:217], v147 offset:128
	s_waitcnt lgkmcnt(3)
	v_pk_mul_f32 v[14:15], v[14:15], v[152:153]
	s_waitcnt lgkmcnt(2)
	v_pk_mul_f32 v[10:11], v[10:11], v[156:157]
	s_waitcnt lgkmcnt(1)
	v_pk_mul_f32 v[6:7], v[6:7], v[210:211]
	v_pk_mul_f32 v[16:17], v[16:17], v[154:155]
	v_pk_mul_f32 v[12:13], v[12:13], v[158:159]
	v_pk_mul_f32 v[8:9], v[8:9], v[212:213]
	s_waitcnt lgkmcnt(0)
	v_pk_mul_f32 v[4:5], v[4:5], v[216:217]
	v_pk_mul_f32 v[2:3], v[2:3], v[214:215]
	v_pk_mul_f32 v[62:63], v[62:63], v[152:153]
	v_pk_mul_f32 v[58:59], v[58:59], v[156:157]
	v_pk_mul_f32 v[54:55], v[54:55], v[210:211]
	v_pk_mul_f32 v[64:65], v[64:65], v[154:155]
	v_pk_mul_f32 v[60:61], v[60:61], v[158:159]
	v_pk_mul_f32 v[56:57], v[56:57], v[212:213]
	v_pk_mul_f32 v[52:53], v[52:53], v[216:217]
	v_pk_mul_f32 v[50:51], v[50:51], v[214:215]
	v_pk_mul_f32 v[46:47], v[46:47], v[152:153]
	v_pk_mul_f32 v[42:43], v[42:43], v[156:157]
	v_pk_mul_f32 v[38:39], v[38:39], v[210:211]
	v_pk_mul_f32 v[48:49], v[48:49], v[154:155]
	v_pk_mul_f32 v[44:45], v[44:45], v[158:159]
	v_pk_mul_f32 v[40:41], v[40:41], v[212:213]
	v_pk_mul_f32 v[36:37], v[36:37], v[216:217]
	v_pk_mul_f32 v[34:35], v[34:35], v[214:215]
	v_pk_mul_f32 v[30:31], v[30:31], v[152:153]
	v_pk_mul_f32 v[26:27], v[26:27], v[156:157]
	v_pk_mul_f32 v[22:23], v[22:23], v[210:211]
	v_pk_mul_f32 v[32:33], v[32:33], v[154:155]
	v_pk_mul_f32 v[28:29], v[28:29], v[158:159]
	v_pk_mul_f32 v[24:25], v[24:25], v[212:213]
	v_pk_mul_f32 v[20:21], v[20:21], v[216:217]
	v_pk_mul_f32 v[18:19], v[18:19], v[214:215]
; #define SBAR() __builtin_amdgcn_sched_barrier(0)
; __device__ __forceinline__ void partialSM(f32x16& p0, f32x16& p1, float& m_reg, float& mn, float& alpha) {
;     ...
;   else { mn = fmaxf(m_reg, pmax); alpha = __builtin_amdgcn_exp2f((m_reg - mn) * C); m_reg = mn; }
;   float mnC = -mn * C;
; #pragma unroll
;   for (int r = 0; r < 16; ++r) p0[r] = fmaf(p0[r], C, mnC);
; #pragma unroll
;   for (int r = 0; r < 16; ++r) p1[r] = fmaf(p1[r], C, mnC);
; #pragma unroll
;   for (int r = 0; r < 16; ++r) p0[r] = __builtin_amdgcn_exp2f(p0[r]);
; template <bool META>
; __device__ __forceinline__ void attn_unit(const bf16_t* Q, bf16_t* Oo, const bf16_t* __restrict__ Kb, const bf16_t* __restrict__ Vb, int b, int kvh, int h, int qb, char* lds, const int tid, const float* qn, const float* RT) {
;     ...
;     SBAR(); qkt(pA0, pA1, (bf16_t*)((char*)K_lds + bn * SHM_K), qr, r32, hi);
;     if (j + 1 == NT - 1) mask_last(pA0, pA1);
;     finishSM(pB0, pB1, alB, l_reg, pa0, pa1, pa2, pa3); SBAR();
.LBB0_264:
	v_cndmask_b32_e64 v209, v146, v150, s[42:43]
	v_mul_f32_e32 v154, 0xbe0293ee, v209
	s_add_i32 s4, s4, 2
	v_fmamk_f32 v82, v82, 0x3e0293ee, v154
	v_fmamk_f32 v83, v83, 0x3e0293ee, v154
	v_fmamk_f32 v84, v84, 0x3e0293ee, v154
	v_fmamk_f32 v85, v85, 0x3e0293ee, v154
	v_fmamk_f32 v86, v86, 0x3e0293ee, v154
	v_fmamk_f32 v87, v87, 0x3e0293ee, v154
	v_fmamk_f32 v88, v88, 0x3e0293ee, v154
	v_fmamk_f32 v89, v89, 0x3e0293ee, v154
	v_fmamk_f32 v90, v90, 0x3e0293ee, v154
	v_fmamk_f32 v91, v91, 0x3e0293ee, v154
	v_fmamk_f32 v92, v92, 0x3e0293ee, v154
	v_fmamk_f32 v93, v93, 0x3e0293ee, v154
	v_fmamk_f32 v94, v94, 0x3e0293ee, v154
	v_fmamk_f32 v95, v95, 0x3e0293ee, v154
	v_fmamk_f32 v96, v96, 0x3e0293ee, v154
	v_fmamk_f32 v97, v97, 0x3e0293ee, v154
	v_fmamk_f32 v155, v66, 0x3e0293ee, v154
	v_fmamk_f32 v156, v67, 0x3e0293ee, v154
	v_fmamk_f32 v157, v68, 0x3e0293ee, v154
	v_fmamk_f32 v158, v69, 0x3e0293ee, v154
	v_fmamk_f32 v159, v70, 0x3e0293ee, v154
	v_fmamk_f32 v160, v71, 0x3e0293ee, v154
	v_fmamk_f32 v161, v72, 0x3e0293ee, v154
	v_fmamk_f32 v198, v73, 0x3e0293ee, v154
	v_fmamk_f32 v199, v74, 0x3e0293ee, v154
	v_fmamk_f32 v200, v75, 0x3e0293ee, v154
	v_fmamk_f32 v201, v76, 0x3e0293ee, v154
	v_fmamk_f32 v202, v77, 0x3e0293ee, v154
	v_fmamk_f32 v203, v78, 0x3e0293ee, v154
	v_fmamk_f32 v204, v79, 0x3e0293ee, v154
	v_fmamk_f32 v205, v80, 0x3e0293ee, v154
	v_fmac_f32_e32 v154, 0x3e0293ee, v81
	v_exp_f32_e32 v206, v82
	v_exp_f32_e32 v207, v83
	v_exp_f32_e32 v212, v84
	v_exp_f32_e32 v213, v85
	v_exp_f32_e32 v214, v86
	v_exp_f32_e32 v215, v87
	v_exp_f32_e32 v216, v88
	v_exp_f32_e32 v217, v89
	v_exp_f32_e32 v218, v90
	v_exp_f32_e32 v219, v91
	v_exp_f32_e32 v220, v92
	v_exp_f32_e32 v221, v93
	v_exp_f32_e32 v222, v94
	v_exp_f32_e32 v223, v95
	v_exp_f32_e32 v224, v96
	v_exp_f32_e32 v225, v97
	v_add_u32_e32 v211, s10, v182
	s_waitcnt vmcnt(0)
	s_waitcnt lgkmcnt(0)
	s_barrier
	ds_read_b128 v[66:69], v211 offset:49152
	ds_read_b128 v[82:85], v211 offset:50176
	ds_read_b128 v[146:149], v211 offset:51200
	ds_read_b128 v[150:153], v211 offset:52224
	v_exp_f32_e32 v155, v155
	s_waitcnt lgkmcnt(3)
	v_mfma_f32_32x32x16_bf16 v[66:81], v[66:69], v[98:101], 0
	v_exp_f32_e32 v156, v156
	v_exp_f32_e32 v157, v157
	v_exp_f32_e32 v158, v158
	v_exp_f32_e32 v159, v159
	v_exp_f32_e32 v160, v160
	v_exp_f32_e32 v161, v161
	v_exp_f32_e32 v198, v198
	s_waitcnt lgkmcnt(2)
	v_mfma_f32_32x32x16_bf16 v[82:97], v[82:85], v[98:101], 0
	v_exp_f32_e32 v199, v199
	v_exp_f32_e32 v200, v200
	v_exp_f32_e32 v201, v201
	v_exp_f32_e32 v202, v202
	v_exp_f32_e32 v203, v203
	v_exp_f32_e32 v204, v204
	v_exp_f32_e32 v205, v205
	s_waitcnt lgkmcnt(1)
	v_mfma_f32_32x32x16_bf16 v[66:81], v[146:149], v[102:105], v[66:81]
	v_exp_f32_e32 v226, v154
	v_cvt_pk_bf16_f32 v154, v155, v156
	s_waitcnt lgkmcnt(0)
	v_mfma_f32_32x32x16_bf16 v[82:97], v[150:153], v[102:105], v[82:97]
	ds_read_b128 v[146:149], v211 offset:53248
	ds_read_b128 v[150:153], v211 offset:54272
	s_waitcnt lgkmcnt(1)
	v_mfma_f32_32x32x16_bf16 v[66:81], v[146:149], v[106:109], v[66:81]
	s_waitcnt lgkmcnt(0)
	v_mfma_f32_32x32x16_bf16 v[82:97], v[150:153], v[106:109], v[82:97]
	ds_read_b128 v[146:149], v211 offset:55296
	ds_read_b128 v[150:153], v211 offset:56320
	s_waitcnt lgkmcnt(1)
	v_mfma_f32_32x32x16_bf16 v[66:81], v[146:149], v[110:113], v[66:81]
	s_waitcnt lgkmcnt(0)
	v_mfma_f32_32x32x16_bf16 v[82:97], v[150:153], v[110:113], v[82:97]
	ds_read_b128 v[146:149], v211 offset:57344
	ds_read_b128 v[150:153], v211 offset:58368
	s_waitcnt lgkmcnt(1)
	v_mfma_f32_32x32x16_bf16 v[66:81], v[146:149], v[114:117], v[66:81]
	s_waitcnt lgkmcnt(0)
	v_mfma_f32_32x32x16_bf16 v[82:97], v[150:153], v[114:117], v[82:97]
	ds_read_b128 v[146:149], v211 offset:59392
	ds_read_b128 v[150:153], v211 offset:60416
	s_waitcnt lgkmcnt(1)
	v_mfma_f32_32x32x16_bf16 v[66:81], v[146:149], v[118:121], v[66:81]
	s_waitcnt lgkmcnt(0)
	v_mfma_f32_32x32x16_bf16 v[82:97], v[150:153], v[118:121], v[82:97]
	ds_read_b128 v[146:149], v211 offset:61440
	ds_read_b128 v[150:153], v211 offset:62464
	s_waitcnt lgkmcnt(1)
	v_mfma_f32_32x32x16_bf16 v[66:81], v[146:149], v[122:125], v[66:81]
	s_waitcnt lgkmcnt(0)
	v_mfma_f32_32x32x16_bf16 v[82:97], v[150:153], v[122:125], v[82:97]
	ds_read_b128 v[146:149], v211 offset:63488
	ds_read_b128 v[150:153], v211 offset:64512
	s_waitcnt lgkmcnt(1)
	v_mfma_f32_32x32x16_bf16 v[66:81], v[146:149], v[126:129], v[66:81]
	v_add_f32_e32 v146, v207, v206
	v_add_f32_e32 v146, v212, v146
	v_add_f32_e32 v146, v213, v146
	v_add_f32_e32 v146, v214, v146
	v_add_f32_e32 v146, v215, v146
	v_add_f32_e32 v146, v216, v146
	v_add_f32_e32 v146, v217, v146
	v_add_f32_e32 v146, v218, v146
	v_add_f32_e32 v146, v219, v146
	v_add_f32_e32 v146, v220, v146
	v_add_f32_e32 v146, v221, v146
	v_add_f32_e32 v146, v222, v146
	v_add_f32_e32 v146, v223, v146
	v_add_f32_e32 v146, v224, v146
	v_add_f32_e32 v146, v225, v146
	v_add_f32_e32 v146, v155, v146
	v_add_f32_e32 v146, v156, v146
	v_add_f32_e32 v146, v157, v146
	v_add_f32_e32 v146, v158, v146
	v_add_f32_e32 v146, v159, v146
	v_add_f32_e32 v146, v160, v146
	v_add_f32_e32 v146, v161, v146
	v_add_f32_e32 v146, v198, v146
	v_add_f32_e32 v146, v199, v146
	v_add_f32_e32 v146, v200, v146
	s_waitcnt lgkmcnt(0)
	v_mfma_f32_32x32x16_bf16 v[82:97], v[150:153], v[126:129], v[82:97]
	v_add_f32_e32 v146, v201, v146
	v_add_f32_e32 v146, v202, v146
	v_add_f32_e32 v146, v203, v146
	v_add_f32_e32 v146, v204, v146
	v_add_f32_e32 v146, v205, v146
	v_add_f32_e32 v210, v226, v146
	v_mov_b32_e32 v211, v210
	v_cvt_pk_bf16_f32 v146, v206, v207
	v_cvt_pk_bf16_f32 v147, v212, v213
	v_cvt_pk_bf16_f32 v148, v214, v215
	v_cvt_pk_bf16_f32 v149, v216, v217
	v_cvt_pk_bf16_f32 v150, v218, v219
	v_cvt_pk_bf16_f32 v151, v220, v221
	v_cvt_pk_bf16_f32 v152, v222, v223
	v_cvt_pk_bf16_f32 v153, v224, v225
	v_cvt_pk_bf16_f32 v155, v157, v158
	v_cvt_pk_bf16_f32 v156, v159, v160
	v_cvt_pk_bf16_f32 v157, v161, v198
	v_cvt_pk_bf16_f32 v158, v199, v200
	v_cvt_pk_bf16_f32 v159, v201, v202
	v_cvt_pk_bf16_f32 v160, v203, v204
	v_cvt_pk_bf16_f32 v161, v205, v226
	v_permlane32_swap_b32_e32 v210, v211
	v_permlane32_swap_b32_e32 v146, v148
	v_permlane32_swap_b32_e32 v147, v149
	v_permlane32_swap_b32_e32 v150, v152
	v_permlane32_swap_b32_e32 v151, v153
	v_permlane32_swap_b32_e32 v154, v156
	v_permlane32_swap_b32_e32 v155, v157
	v_permlane32_swap_b32_e32 v158, v160
	v_permlane32_swap_b32_e32 v159, v161
	s_and_b64 vcc, exec, s[40:41]
	s_cbranch_vccz .Latt_nomask
	v_mov_b32_e32 v74, v246
	v_mov_b32_e32 v75, v246
	v_mov_b32_e32 v76, v246
	v_mov_b32_e32 v77, v246
	v_mov_b32_e32 v78, v246
	v_mov_b32_e32 v79, v246
	v_mov_b32_e32 v80, v246
	v_mov_b32_e32 v81, v246
	v_mov_b32_e32 v82, v246
	v_mov_b32_e32 v83, v246
	v_mov_b32_e32 v84, v246
	v_mov_b32_e32 v85, v246
	v_mov_b32_e32 v86, v246
	v_mov_b32_e32 v87, v246
	v_mov_b32_e32 v88, v246
	v_mov_b32_e32 v89, v246
	v_mov_b32_e32 v90, v246
	v_mov_b32_e32 v91, v246
	v_mov_b32_e32 v92, v246
	v_mov_b32_e32 v93, v246
	v_mov_b32_e32 v94, v246
	v_mov_b32_e32 v95, v246
	v_mov_b32_e32 v96, v246
	v_mov_b32_e32 v97, v246

; #define SWRITE(bb, i) do { *(bf16x8*)((char*)V_lds + (bb) * SHM_V + vst0) = sr_[i].vs0;          \
;     *(bf16x8*)((char*)V_lds + (bb) * SHM_V + vst1) = sr_[i].vs1; int kc = sc * 2;               \
;     *(bf16x8*)((char*)K_lds + (bb) * SHM_K + KSWZ(sr, kc)) = sr_[i].ks0;                       \
;     *(bf16x8*)((char*)K_lds + (bb) * SHM_K + KSWZ(32 + sr, kc)) = sr_[i].ks1; } while (0)
; #define SWAIT() asm volatile("s_waitcnt vmcnt(0)" ::: "memory")
; #define RESC(a) do { if (__any((a) < 1.f)) { if (hi == 0) al_l[r32] = (a); asm volatile("s_waitcnt lgkmcnt(0)" ::: "memory"); \
;     _Pragma("unroll") for (int d = 0; d < 4; ++d) _Pragma("unroll") for (int r = 0; r < 16; ++r) o[d][r] *= al_l[crow(r, hi)]; } } while (0)
; __device__ __forceinline__ void partialSM(f32x16& p0, f32x16& p1, float& m_reg, float& mn, float& alpha) {
;     ...
;   else { mn = fmaxf(m_reg, pmax); alpha = __builtin_amdgcn_exp2f((m_reg - mn) * C); m_reg = mn; }
;   float mnC = -mn * C;
; #pragma unroll
;   for (int r = 0; r < 16; ++r) p0[r] = fmaf(p0[r], C, mnC);
; #pragma unroll
;   for (int r = 0; r < 16; ++r) p1[r] = fmaf(p1[r], C, mnC);
; template <bool META>
; __device__ __forceinline__ void attn_unit(const bf16_t* Q, bf16_t* Oo, const bf16_t* __restrict__ Kb, const bf16_t* __restrict__ Vb, int b, int kvh, int h, int qb, char* lds, const int tid, const float* qn, const float* RT) {
;     ...
;     pv_d0(o, vb0 + bc * (int)SHM_V, pa0, pa1, pa2, pa3); partialSM(pA0, pA1, m_reg, mnA, alA);
;     SWAIT(); SWRITE(bp, SO);
;     RESC(alA); __syncthreads();
;     bc = bp;
.LBB0_270:
	v_cndmask_b32_e64 v150, v231, v209, s[40:41]
	v_mul_f32_e32 v232, 0xbe0293ee, v150
	v_mov_b32_e32 v158, v232
	v_fmamk_f32 v66, v66, 0x3e0293ee, v232
	v_fmamk_f32 v67, v67, 0x3e0293ee, v232
	v_fmamk_f32 v68, v68, 0x3e0293ee, v232
	v_fmamk_f32 v69, v69, 0x3e0293ee, v232
	v_fmamk_f32 v70, v70, 0x3e0293ee, v232
	v_fmamk_f32 v71, v71, 0x3e0293ee, v232
	v_fmamk_f32 v72, v72, 0x3e0293ee, v232
	v_fmamk_f32 v73, v73, 0x3e0293ee, v232
	v_fmamk_f32 v231, v74, 0x3e0293ee, v232
	v_fmamk_f32 v233, v75, 0x3e0293ee, v232
	v_fmamk_f32 v234, v76, 0x3e0293ee, v232
	v_fmamk_f32 v235, v77, 0x3e0293ee, v232
	v_fmamk_f32 v236, v78, 0x3e0293ee, v232
	v_fmamk_f32 v237, v79, 0x3e0293ee, v232
	v_fmamk_f32 v156, v80, 0x3e0293ee, v232
	v_fmac_f32_e32 v158, 0x3e0293ee, v81
	v_exp_f32_e32 v146, v66
	v_exp_f32_e32 v147, v67
	v_exp_f32_e32 v148, v68
	v_exp_f32_e32 v159, v69
	v_exp_f32_e32 v160, v70
	v_exp_f32_e32 v209, v71
	v_exp_f32_e32 v149, v72
	v_exp_f32_e32 v161, v73
	v_exp_f32_e32 v151, v231
	v_exp_f32_e32 v153, v233
	v_exp_f32_e32 v154, v234
	v_exp_f32_e32 v157, v235
	v_exp_f32_e32 v152, v236
	v_exp_f32_e32 v155, v237
	v_exp_f32_e32 v156, v156
	v_exp_f32_e32 v158, v158
	v_add_f32_e32 v66, v193, v195
	s_add_u32 s90, s90, 0x80
	v_fmac_f32_e32 v66, v192, v0
	v_add_f32_e32 v0, v210, v211
	s_addc_u32 s91, s91, 0
	v_pk_fma_f32 v[144:145], v[82:83], s[36:37], v[232:233] op_sel_hi:[1,0,0]
	v_pk_fma_f32 v[142:143], v[84:85], s[36:37], v[232:233] op_sel_hi:[1,0,0]
	v_pk_fma_f32 v[140:141], v[86:87], s[36:37], v[232:233] op_sel_hi:[1,0,0]
	v_pk_fma_f32 v[138:139], v[88:89], s[36:37], v[232:233] op_sel_hi:[1,0,0]
	v_pk_fma_f32 v[136:137], v[90:91], s[36:37], v[232:233] op_sel_hi:[1,0,0]
	v_pk_fma_f32 v[134:135], v[92:93], s[36:37], v[232:233] op_sel_hi:[1,0,0]
	v_pk_fma_f32 v[132:133], v[94:95], s[36:37], v[232:233] op_sel_hi:[1,0,0]
	v_pk_fma_f32 v[130:131], v[96:97], s[36:37], v[232:233] op_sel_hi:[1,0,0]
	v_fmac_f32_e32 v0, v66, v196
	s_cmpk_gt_u32 s4, 0xfd
	s_cbranch_scc1 .Lrot_exit
	s_mov_b32 s6, s28
	v_sub_co_u32_e64 v66, s[0:1], s6, 1
	s_and_b64 s[0:1], s[0:1], exec
	v_readfirstlane_b32 s0, v66
	s_cselect_b32 s28, 2, s0
	s_lshl_b32 s9, s6, 14
	s_add_i32 s0, s9, 0
	v_add_u32_e32 v195, s0, v182
	v_mov_b32_e32 v192, v230
	s_waitcnt vmcnt(0)
	s_waitcnt lgkmcnt(0)
	s_barrier
	s_branch .LBB0_260
.Lrot_exit:
	s_waitcnt vmcnt(0)
	s_waitcnt lgkmcnt(0)
	s_barrier
